# v19 + G1 epilogue: bj=1 bias pair loaded with the bj=0 pair at the epilogue top and copied into v[64:71] at the old load site (removes one exposed load round trip per tile)
# speedup vs baseline: 1.0058x; 1.0058x over previous
.LBB0_105:
	s_lshl_b32 s2, s34, 8
	v_mov_b32_e32 v148, v162
	v_mov_b32_e32 v104, v163
	s_or_b32 s2, s2, s45
	v_readlane_b32 s56, v254, 7
	v_lshl_add_u32 v160, v104, 3, s2
	v_ashrrev_i32_e32 v161, 31, v160
	v_readlane_b32 s66, v254, 17
	v_readlane_b32 s67, v254, 18
	s_cmp_gt_i32 s34, 7
	s_cselect_b64 s[2:3], -1, 0
	v_lshl_add_u64 v[158:159], v[160:161], 2, s[66:67]
	global_load_dwordx4 v[108:111], v[158:159], off
	global_load_dwordx4 v[104:107], v[158:159], off offset:16
	global_load_dwordx4 v[228:231], v[158:159], off offset:512
	global_load_dwordx4 v[232:235], v[158:159], off offset:528
	s_mov_b64 s[36:37], -1
	s_and_b64 vcc, exec, s[2:3]
	v_readlane_b32 s57, v254, 8
	v_readlane_b32 s58, v254, 9
	v_readlane_b32 s59, v254, 10
	v_readlane_b32 s60, v254, 11
	v_readlane_b32 s61, v254, 12
	v_readlane_b32 s62, v254, 13
	v_readlane_b32 s63, v254, 14
	v_readlane_b32 s64, v254, 15
	v_readlane_b32 s65, v254, 16
	v_readlane_b32 s68, v254, 19
	v_readlane_b32 s69, v254, 20
	v_readlane_b32 s70, v254, 21
	v_readlane_b32 s71, v254, 22
	s_waitcnt vmcnt(0)
	v_pk_add_f32 v[134:135], v[134:135], v[110:111]
	v_pk_add_f32 v[132:133], v[132:133], v[108:109]
	v_pk_add_f32 v[130:131], v[130:131], v[106:107]
	v_pk_add_f32 v[128:129], v[128:129], v[104:105]
	s_cbranch_vccz .LBB0_107
	v_cvt_pk_bf16_f32 v136, v132, v133
	v_cvt_pk_bf16_f32 v137, v134, v135
	v_cvt_pk_bf16_f32 v138, v128, v129
	v_cvt_pk_bf16_f32 v139, v130, v131
	s_mov_b64 s[36:37], 0

.LBB0_137:
	v_add_u32_e32 v72, 0xb0, v128
	v_ashrrev_i32_e32 v73, 31, v72
	s_add_u32 s2, s90, s2
	s_addc_u32 s3, s91, s3
	v_lshlrev_b64 v[68:69], 12, v[72:73]
	v_lshl_add_u64 v[68:69], s[2:3], 0, v[68:69]
	v_lshl_add_u64 v[68:69], v[68:69], 0, v[148:149]
	global_store_dwordx4 v[68:69], v[64:67], off
	s_and_b64 vcc, exec, s[6:7]
	s_mov_b64 s[2:3], -1
	s_nop 1
	v_mov_b32_e32 v68, v228
	v_mov_b32_e32 v69, v229
	v_mov_b32_e32 v70, v230
	v_mov_b32_e32 v71, v231
	v_mov_b32_e32 v64, v232
	v_mov_b32_e32 v65, v233
	v_mov_b32_e32 v66, v234
	v_mov_b32_e32 v67, v235
	v_pk_add_f32 v[62:63], v[62:63], v[70:71]
	v_pk_add_f32 v[78:79], v[60:61], v[68:69]
	v_pk_add_f32 v[60:61], v[58:59], v[66:67]
	v_pk_add_f32 v[74:75], v[56:57], v[64:65]
	s_cbranch_vccnz .LBB0_139
	s_mov_b64 s[2:3], 0
	v_cvt_pk_bf16_f32 v56, v78, v79
	v_cvt_pk_bf16_f32 v57, v62, v63
	v_cvt_pk_bf16_f32 v58, v74, v75
	v_cvt_pk_bf16_f32 v59, v60, v61
